# attention: packed f32 softmax math, permlane-swap row reductions, normalisation after PV, P^T packed in place, one workgroup barrier per query tile
# baseline (speedup 1.0000x reference)
; __device__ __forceinline__ void unpack8(const u32x4 w, f32x4& a, f32x4& b) { a[0] = bf_lo(w.x); a[1] = bf_hi(w.x); a[2] = bf_lo(w.y); a[3] = bf_hi(w.y); b[0] = bf_lo(w.z); b[1] = bf_hi(w.z); b[2] = bf_lo(w.w); b[3] = bf_hi(w.w); }
; __device__ __forceinline__ void phase_ln(const float* RES, const bf16_t* DEL, float* X, bf16_t* XB, const float* g, const float* b, bool write_xb) {
;     ...
;     for (int base = w0; base < M_TOK; base += nw * 4) {
;         f32x4 v[4][4];
; #pragma unroll
;         for (int r = 0; r < 4; ++r) { const float* xr = RES + (size_t)(base + r * nw) * 1024; const bf16_t* dr = DEL + (size_t)(base + r * nw) * 1024;
; #pragma unroll
;             for (int i = 0; i < 2; ++i) { const int c = i * 512 + lane * 8; const f32x4 xa = *(const f32x4*)(xr + c), xb2 = *(const f32x4*)(xr + c + 4); const u32x4 d4 = *(const u32x4*)(dr + c);
;                 f32x4 da, db; unpack8(d4, da, db); v[r][2 * i] = xa * ALPHA + da; v[r][2 * i + 1] = xb2 * ALPHA + db; } }
.LBB0_220:
	v_ashrrev_i32_e32 v1, 31, v0
	v_lshlrev_b64 v[2:3], 12, v[0:1]
	v_lshlrev_b64 v[4:5], 11, v[0:1]
	v_lshl_add_u64 v[2:3], v[34:35], 0, v[2:3]
	v_lshl_add_u64 v[4:5], v[36:37], 0, v[4:5]
	global_load_dwordx4 v[138:141], v[2:3], off offset:16
	global_load_dwordx4 v[142:145], v[2:3], off
	global_load_dwordx4 v[146:149], v[4:5], off
	global_load_dwordx4 v[150:153], v[2:3], off offset:2064
	global_load_dwordx4 v[154:157], v[2:3], off offset:2048
	global_load_dwordx4 v[158:161], v[4:5], off offset:1024
	v_add_u32_e32 v6, s16, v0
	v_ashrrev_i32_e32 v7, 31, v6
	v_lshlrev_b64 v[2:3], 12, v[6:7]
	v_lshlrev_b64 v[4:5], 11, v[6:7]
	v_lshl_add_u64 v[2:3], v[34:35], 0, v[2:3]
	v_lshl_add_u64 v[4:5], v[36:37], 0, v[4:5]
	global_load_dwordx4 v[162:165], v[2:3], off offset:16
	global_load_dwordx4 v[166:169], v[2:3], off
	global_load_dwordx4 v[170:173], v[4:5], off
	global_load_dwordx4 v[174:177], v[2:3], off offset:2064
	global_load_dwordx4 v[186:189], v[2:3], off offset:2048
	global_load_dwordx4 v[194:197], v[4:5], off offset:1024
	v_add_u32_e32 v6, s25, v0
	v_ashrrev_i32_e32 v7, 31, v6
	v_lshlrev_b64 v[2:3], 12, v[6:7]
	v_lshlrev_b64 v[4:5], 11, v[6:7]
	v_lshl_add_u64 v[2:3], v[34:35], 0, v[2:3]
	v_lshl_add_u64 v[4:5], v[36:37], 0, v[4:5]
	global_load_dwordx4 v[198:201], v[2:3], off offset:16
	global_load_dwordx4 v[202:205], v[2:3], off
	global_load_dwordx4 v[206:209], v[4:5], off
	global_load_dwordx4 v[210:213], v[2:3], off offset:2064
	global_load_dwordx4 v[220:223], v[2:3], off offset:2048
	global_load_dwordx4 v[224:227], v[4:5], off offset:1024
	v_add_u32_e32 v6, s48, v0
	v_ashrrev_i32_e32 v7, 31, v6
	v_lshlrev_b64 v[2:3], 12, v[6:7]
	v_lshlrev_b64 v[4:5], 11, v[6:7]
	v_lshl_add_u64 v[2:3], v[34:35], 0, v[2:3]
	v_lshl_add_u64 v[4:5], v[36:37], 0, v[4:5]
	global_load_dwordx4 v[228:231], v[2:3], off offset:16
	global_load_dwordx4 v[232:235], v[2:3], off
	global_load_dwordx4 v[236:239], v[4:5], off
	global_load_dwordx4 v[244:247], v[2:3], off offset:2064
	global_load_dwordx4 v[248:251], v[2:3], off offset:2048
	v_mov_b32_e32 v8, v4
	v_mov_b32_e32 v9, v5
	v_add_u32_e32 v80, s25, v0
	v_ashrrev_i32_e32 v81, 31, v80
	v_add_u32_e32 v84, s48, v0
	v_ashrrev_i32_e32 v85, 31, v84
	v_lshlrev_b64 v[38:39], 10, v[0:1]
	v_or_b32_e32 v134, v38, v26
	v_mov_b32_e32 v135, v39
	v_cndmask_b32_e64 v13, 0, 1, s[42:43]
	v_cmp_ne_u32_e64 s[38:39], 1, v13
	s_waitcnt vmcnt(20)
	v_lshlrev_b32_e32 v20, 16, v146
	v_and_b32_e32 v21, 0xffff0000, v146
	v_lshlrev_b32_e32 v14, 16, v147
	v_and_b32_e32 v15, 0xffff0000, v147
	v_lshlrev_b32_e32 v24, 16, v148
	v_and_b32_e32 v25, 0xffff0000, v148
	v_lshlrev_b32_e32 v16, 16, v149
	v_and_b32_e32 v17, 0xffff0000, v149
	v_pk_fma_f32 v[18:19], v[144:145], s[4:5], v[14:15] op_sel_hi:[1,0,1]
	v_pk_fma_f32 v[20:21], v[142:143], s[4:5], v[20:21] op_sel_hi:[1,0,1]
	v_pk_fma_f32 v[22:23], v[140:141], s[4:5], v[16:17] op_sel_hi:[1,0,1]
	v_pk_fma_f32 v[24:25], v[138:139], s[4:5], v[24:25] op_sel_hi:[1,0,1]
	global_load_dwordx4 v[146:149], v[8:9], off offset:1024
	s_waitcnt vmcnt(18)
	v_lshlrev_b32_e32 v40, 16, v160
	v_and_b32_e32 v41, 0xffff0000, v160
	v_pk_fma_f32 v[46:47], v[150:151], s[4:5], v[40:41] op_sel_hi:[1,0,1]
	v_add_u32_e32 v40, s16, v0
	v_lshlrev_b32_e32 v10, 16, v158
	v_and_b32_e32 v11, 0xffff0000, v158
	v_lshlrev_b32_e32 v14, 16, v159
	v_and_b32_e32 v15, 0xffff0000, v159
	v_ashrrev_i32_e32 v41, 31, v40
	v_pk_fma_f32 v[44:45], v[156:157], s[4:5], v[14:15] op_sel_hi:[1,0,1]
	v_lshlrev_b32_e32 v16, 16, v161
	v_and_b32_e32 v17, 0xffff0000, v161
	v_pk_fma_f32 v[48:49], v[154:155], s[4:5], v[10:11] op_sel_hi:[1,0,1]
	v_pk_fma_f32 v[42:43], v[152:153], s[4:5], v[16:17] op_sel_hi:[1,0,1]
	s_waitcnt vmcnt(15)
	v_lshlrev_b32_e32 v52, 16, v170
	v_and_b32_e32 v53, 0xffff0000, v170
	v_lshlrev_b32_e32 v14, 16, v171
	v_and_b32_e32 v15, 0xffff0000, v171
	v_lshlrev_b32_e32 v54, 16, v172
	v_and_b32_e32 v55, 0xffff0000, v172
	v_lshlrev_b32_e32 v16, 16, v173
	v_and_b32_e32 v17, 0xffff0000, v173
	v_pk_fma_f32 v[70:71], v[168:169], s[4:5], v[14:15] op_sel_hi:[1,0,1]
	v_pk_fma_f32 v[72:73], v[166:167], s[4:5], v[52:53] op_sel_hi:[1,0,1]
	v_pk_fma_f32 v[66:67], v[164:165], s[4:5], v[16:17] op_sel_hi:[1,0,1]
	v_pk_fma_f32 v[68:69], v[162:163], s[4:5], v[54:55] op_sel_hi:[1,0,1]
	s_waitcnt vmcnt(12)
	v_lshlrev_b32_e32 v10, 16, v194
	v_and_b32_e32 v11, 0xffff0000, v194
	v_lshlrev_b32_e32 v14, 16, v195
	v_and_b32_e32 v15, 0xffff0000, v195
	v_lshlrev_b32_e32 v52, 16, v196
	v_and_b32_e32 v53, 0xffff0000, v196
	v_pk_fma_f32 v[54:55], v[188:189], s[4:5], v[14:15] op_sel_hi:[1,0,1]
	v_pk_fma_f32 v[52:53], v[174:175], s[4:5], v[52:53] op_sel_hi:[1,0,1]
	v_lshlrev_b32_e32 v16, 16, v197
	v_and_b32_e32 v17, 0xffff0000, v197
	v_pk_fma_f32 v[56:57], v[186:187], s[4:5], v[10:11] op_sel_hi:[1,0,1]
	v_pk_fma_f32 v[50:51], v[176:177], s[4:5], v[16:17] op_sel_hi:[1,0,1]
	s_waitcnt vmcnt(9)
	v_lshlrev_b32_e32 v60, 16, v206
	v_and_b32_e32 v61, 0xffff0000, v206
	v_lshlrev_b32_e32 v14, 16, v207
	v_and_b32_e32 v15, 0xffff0000, v207
	v_lshlrev_b32_e32 v62, 16, v208
	v_and_b32_e32 v63, 0xffff0000, v208
	v_lshlrev_b32_e32 v16, 16, v209
	v_and_b32_e32 v17, 0xffff0000, v209
	v_pk_fma_f32 v[78:79], v[204:205], s[4:5], v[14:15] op_sel_hi:[1,0,1]
	v_pk_fma_f32 v[82:83], v[202:203], s[4:5], v[60:61] op_sel_hi:[1,0,1]
	v_pk_fma_f32 v[74:75], v[200:201], s[4:5], v[16:17] op_sel_hi:[1,0,1]
	v_pk_fma_f32 v[76:77], v[198:199], s[4:5], v[62:63] op_sel_hi:[1,0,1]
	s_waitcnt vmcnt(6)
; __device__ __forceinline__ void phase_ln(const float* RES, const bf16_t* DEL, float* X, bf16_t* XB, const float* g, const float* b, bool write_xb) {
;     ...
;         for (int r = 0; r < 4; ++r) { float s = 0.f;
; #pragma unroll
;             for (int i = 0; i < 4; ++i) s += v[r][i][0] + v[r][i][1] + v[r][i][2] + v[r][i][3];
;             mean[r] = wave_sum(s) * (1.f / 1024.f); }
; #pragma unroll
;         for (int r = 0; r < 4; ++r) { float q = 0.f;
; #pragma unroll
;             for (int i = 0; i < 4; ++i) { v[r][i] -= mean[r]; q += v[r][i][0] * v[r][i][0] + v[r][i][1] * v[r][i][1] + v[r][i][2] * v[r][i][2] + v[r][i][3] * v[r][i][3]; }
;             rs[r] = rsqrtf(wave_sum(q) * (1.f / 1024.f) + 1e-5f); }
	v_lshlrev_b32_e32 v10, 16, v224
	v_and_b32_e32 v11, 0xffff0000, v224
	v_lshlrev_b32_e32 v14, 16, v225
	v_and_b32_e32 v15, 0xffff0000, v225
	v_lshlrev_b32_e32 v60, 16, v226
	v_and_b32_e32 v61, 0xffff0000, v226
	v_lshlrev_b32_e32 v16, 16, v227
	v_and_b32_e32 v17, 0xffff0000, v227
	v_pk_fma_f32 v[62:63], v[222:223], s[4:5], v[14:15] op_sel_hi:[1,0,1]
	v_pk_fma_f32 v[58:59], v[212:213], s[4:5], v[16:17] op_sel_hi:[1,0,1]
	v_pk_fma_f32 v[64:65], v[220:221], s[4:5], v[10:11] op_sel_hi:[1,0,1]
	v_pk_fma_f32 v[60:61], v[210:211], s[4:5], v[60:61] op_sel_hi:[1,0,1]
	s_waitcnt vmcnt(3)
	v_lshlrev_b32_e32 v86, 16, v236
	v_and_b32_e32 v87, 0xffff0000, v236
	v_lshlrev_b32_e32 v8, 16, v237
	v_and_b32_e32 v9, 0xffff0000, v237
	v_lshlrev_b32_e32 v88, 16, v238
	v_and_b32_e32 v89, 0xffff0000, v238
	v_lshlrev_b32_e32 v10, 16, v239
	v_and_b32_e32 v11, 0xffff0000, v239
	v_pk_fma_f32 v[90:91], v[234:235], s[4:5], v[8:9] op_sel_hi:[1,0,1]
	v_pk_fma_f32 v[92:93], v[232:233], s[4:5], v[86:87] op_sel_hi:[1,0,1]
	v_pk_fma_f32 v[86:87], v[230:231], s[4:5], v[10:11] op_sel_hi:[1,0,1]
	v_pk_fma_f32 v[88:89], v[228:229], s[4:5], v[88:89] op_sel_hi:[1,0,1]
	s_waitcnt vmcnt(0)
	v_lshlrev_b32_e32 v16, 16, v148
	v_and_b32_e32 v17, 0xffff0000, v148
	v_lshlrev_b32_e32 v10, 16, v149
	v_and_b32_e32 v11, 0xffff0000, v149
	v_pk_fma_f32 v[94:95], v[246:247], s[4:5], v[10:11] op_sel_hi:[1,0,1]
	v_pk_fma_f32 v[98:99], v[244:245], s[4:5], v[16:17] op_sel_hi:[1,0,1]
	v_mov_b32_e32 v0, v24
	v_mov_b32_e32 v1, v20
	v_mov_b32_e32 v2, v25
	v_mov_b32_e32 v3, v21
	v_pk_add_f32 v[0:1], v[0:1], v[2:3]
	v_mov_b32_e32 v2, v22
	v_mov_b32_e32 v3, v18
	v_pk_add_f32 v[0:1], v[2:3], v[0:1]
	v_mov_b32_e32 v2, v23
	v_mov_b32_e32 v3, v19
	v_pk_add_f32 v[0:1], v[2:3], v[0:1]
	v_lshlrev_b32_e32 v14, 16, v146
	v_and_b32_e32 v15, 0xffff0000, v146
	v_add_f32_e32 v1, 0, v1
	v_pk_fma_f32 v[100:101], v[248:249], s[4:5], v[14:15] op_sel_hi:[1,0,1]
	v_add_f32_e32 v4, v0, v1
	v_mov_b32_e32 v0, v46
	v_mov_b32_e32 v1, v48
	v_mov_b32_e32 v2, v47
	v_mov_b32_e32 v3, v49
	v_pk_add_f32 v[0:1], v[0:1], v[2:3]
	v_mov_b32_e32 v2, v42
	v_mov_b32_e32 v3, v44
	v_pk_add_f32 v[0:1], v[2:3], v[0:1]
	v_mov_b32_e32 v2, v43
	v_mov_b32_e32 v3, v45
	v_pk_add_f32 v[0:1], v[2:3], v[0:1]
	v_mov_b32_e32 v2, v69
	v_add_f32_e32 v1, v4, v1
	v_add_f32_e32 v0, v0, v1
	v_mov_b32_e32 v3, v73
	v_lshlrev_b32_e32 v8, 16, v147
	v_add_f32_dpp v0, v0, v0 quad_perm:[1,0,3,2] row_mask:0xf bank_mask:0xf bound_ctrl:1
	v_and_b32_e32 v9, 0xffff0000, v147
	v_pk_fma_f32 v[96:97], v[250:251], s[4:5], v[8:9] op_sel_hi:[1,0,1]
	v_add_f32_dpp v0, v0, v0 quad_perm:[2,3,0,1] row_mask:0xf bank_mask:0xf bound_ctrl:1
	s_nop 1
	v_add_f32_dpp v0, v0, v0 row_half_mirror row_mask:0xf bank_mask:0xf bound_ctrl:1
	s_nop 1
	v_add_f32_dpp v0, v0, v0 row_mirror row_mask:0xf bank_mask:0xf bound_ctrl:1
	s_nop 0
	v_readlane_b32 s2, v0, 16
	v_readlane_b32 s13, v0, 48
	v_readlane_b32 s0, v0, 0
	v_readlane_b32 s1, v0, 32
	v_mov_b32_e32 v0, s2
	v_mov_b32_e32 v1, s13
	v_pk_add_f32 v[0:1], s[0:1], v[0:1]
	s_nop 0
	v_add_f32_e32 v4, v0, v1
	v_mov_b32_e32 v0, v68
	v_mov_b32_e32 v1, v72
	v_pk_add_f32 v[0:1], v[0:1], v[2:3]
	v_mov_b32_e32 v2, v66
	v_mov_b32_e32 v3, v70
	v_pk_add_f32 v[0:1], v[2:3], v[0:1]
	v_mov_b32_e32 v2, v67
	v_mov_b32_e32 v3, v71
	v_pk_add_f32 v[0:1], v[2:3], v[0:1]
	v_mov_b32_e32 v2, v53
	v_add_f32_e32 v1, 0, v1
	v_add_f32_e32 v5, v0, v1
	v_mov_b32_e32 v0, v52
	v_mov_b32_e32 v1, v56
	v_mov_b32_e32 v3, v57
	v_pk_add_f32 v[0:1], v[0:1], v[2:3]
	v_mov_b32_e32 v2, v50
	v_mov_b32_e32 v3, v54
	v_pk_add_f32 v[0:1], v[2:3], v[0:1]
	v_mov_b32_e32 v2, v51
	v_mov_b32_e32 v3, v55
	v_pk_add_f32 v[0:1], v[2:3], v[0:1]
	v_mov_b32_e32 v2, v77
	v_add_f32_e32 v1, v5, v1
	v_add_f32_e32 v0, v0, v1
	v_mov_b32_e32 v3, v83
	v_fmamk_f32 v21, v4, 0xba800000, v21
	v_add_f32_dpp v0, v0, v0 quad_perm:[1,0,3,2] row_mask:0xf bank_mask:0xf bound_ctrl:1
	v_fmamk_f32 v25, v4, 0xba800000, v25
	v_fmac_f32_e32 v20, 0xba800000, v4
	v_add_f32_dpp v0, v0, v0 quad_perm:[2,3,0,1] row_mask:0xf bank_mask:0xf bound_ctrl:1
	v_fmac_f32_e32 v24, 0xba800000, v4
	v_fmac_f32_e32 v18, 0xba800000, v4
	v_add_f32_dpp v0, v0, v0 row_half_mirror row_mask:0xf bank_mask:0xf bound_ctrl:1
	v_fmac_f32_e32 v22, 0xba800000, v4
	v_fmamk_f32 v19, v4, 0xba800000, v19
	v_add_f32_dpp v0, v0, v0 row_mirror row_mask:0xf bank_mask:0xf bound_ctrl:1
	v_fmamk_f32 v23, v4, 0xba800000, v23
	v_readlane_b32 s2, v0, 16
	v_readlane_b32 s13, v0, 48
	v_readlane_b32 s0, v0, 0
	v_readlane_b32 s1, v0, 32
	v_mov_b32_e32 v0, s2
	v_mov_b32_e32 v1, s13
	v_pk_add_f32 v[0:1], s[0:1], v[0:1]
	v_fmamk_f32 v111, v4, 0xba800000, v49
	v_add_f32_e32 v5, v0, v1
	v_mov_b32_e32 v0, v76
	v_mov_b32_e32 v1, v82
	v_pk_add_f32 v[0:1], v[0:1], v[2:3]
	v_mov_b32_e32 v2, v74
	v_mov_b32_e32 v3, v78
	v_pk_add_f32 v[0:1], v[2:3], v[0:1]
	v_mov_b32_e32 v2, v75
	v_mov_b32_e32 v3, v79
	v_pk_add_f32 v[0:1], v[2:3], v[0:1]
	v_mov_b32_e32 v2, v61
	v_add_f32_e32 v1, 0, v1
	v_add_f32_e32 v6, v0, v1
	v_mov_b32_e32 v0, v60
	v_mov_b32_e32 v1, v64
	v_mov_b32_e32 v3, v65
	v_pk_add_f32 v[0:1], v[0:1], v[2:3]
	v_mov_b32_e32 v2, v58
	v_mov_b32_e32 v3, v62
	v_pk_add_f32 v[0:1], v[2:3], v[0:1]
	v_mov_b32_e32 v2, v59
	v_mov_b32_e32 v3, v63
	v_pk_add_f32 v[0:1], v[2:3], v[0:1]
	v_mov_b32_e32 v2, v89
	v_add_f32_e32 v1, v6, v1
	v_add_f32_e32 v0, v0, v1
	v_mov_b32_e32 v3, v93
	v_fmac_f32_e32 v48, 0xba800000, v4
	v_add_f32_dpp v0, v0, v0 quad_perm:[1,0,3,2] row_mask:0xf bank_mask:0xf bound_ctrl:1
	v_fmamk_f32 v110, v4, 0xba800000, v47
	v_fmac_f32_e32 v44, 0xba800000, v4
	v_add_f32_dpp v0, v0, v0 quad_perm:[2,3,0,1] row_mask:0xf bank_mask:0xf bound_ctrl:1
	v_fmac_f32_e32 v46, 0xba800000, v4
; __device__ __forceinline__ void phase_ln(const float* RES, const bf16_t* DEL, float* X, bf16_t* XB, const float* g, const float* b, bool write_xb) {
;     ...
;         for (int r = 0; r < 4; ++r) { float q = 0.f;
; #pragma unroll
;             for (int i = 0; i < 4; ++i) { v[r][i] -= mean[r]; q += v[r][i][0] * v[r][i][0] + v[r][i][1] * v[r][i][1] + v[r][i][2] * v[r][i][2] + v[r][i][3] * v[r][i][3]; }
;             rs[r] = rsqrtf(wave_sum(q) * (1.f / 1024.f) + 1e-5f); }
	v_mov_b32_e32 v47, v48
	v_add_f32_dpp v0, v0, v0 row_half_mirror row_mask:0xf bank_mask:0xf bound_ctrl:1
	v_fmamk_f32 v104, v4, 0xba800000, v43
	v_fmac_f32_e32 v42, 0xba800000, v4
	v_add_f32_dpp v0, v0, v0 row_mirror row_mask:0xf bank_mask:0xf bound_ctrl:1
	v_mov_b32_e32 v43, v44
	v_readlane_b32 s2, v0, 16
	v_readlane_b32 s13, v0, 48
	v_readlane_b32 s0, v0, 0
	v_readlane_b32 s1, v0, 32
	v_mov_b32_e32 v0, s2
	v_mov_b32_e32 v1, s13
	v_pk_add_f32 v[0:1], s[0:1], v[0:1]
	v_fmamk_f32 v105, v4, 0xba800000, v45
	v_add_f32_e32 v6, v0, v1
	v_mov_b32_e32 v0, v88
	v_mov_b32_e32 v1, v92
	v_pk_add_f32 v[0:1], v[0:1], v[2:3]
	v_mov_b32_e32 v2, v86
	v_mov_b32_e32 v3, v90
	v_pk_add_f32 v[0:1], v[2:3], v[0:1]
	v_mov_b32_e32 v2, v87
	v_mov_b32_e32 v3, v91
	v_pk_add_f32 v[0:1], v[2:3], v[0:1]
	v_mov_b32_e32 v2, v99
	v_add_f32_e32 v1, 0, v1
	v_add_f32_e32 v7, v0, v1
	v_mov_b32_e32 v0, v98
	v_mov_b32_e32 v1, v100
	v_mov_b32_e32 v3, v101
	v_pk_add_f32 v[0:1], v[0:1], v[2:3]
	v_mov_b32_e32 v2, v94
	v_mov_b32_e32 v3, v96
	v_pk_add_f32 v[0:1], v[2:3], v[0:1]
	v_mov_b32_e32 v2, v95
	v_mov_b32_e32 v3, v97
	v_pk_add_f32 v[0:1], v[2:3], v[0:1]
	v_mov_b32_e32 v2, v21
	v_add_f32_e32 v1, v7, v1
	v_add_f32_e32 v0, v0, v1
	v_mov_b32_e32 v3, v25
	v_pk_mul_f32 v[2:3], v[2:3], v[2:3]
	v_add_f32_dpp v0, v0, v0 quad_perm:[1,0,3,2] row_mask:0xf bank_mask:0xf bound_ctrl:1
	v_fmamk_f32 v128, v5, 0xba800000, v73
	v_fmamk_f32 v129, v5, 0xba800000, v69
	v_add_f32_dpp v0, v0, v0 quad_perm:[2,3,0,1] row_mask:0xf bank_mask:0xf bound_ctrl:1
	v_fmac_f32_e32 v68, 0xba800000, v5
	v_fmac_f32_e32 v72, 0xba800000, v5
	v_add_f32_dpp v0, v0, v0 row_half_mirror row_mask:0xf bank_mask:0xf bound_ctrl:1
	v_fmac_f32_e32 v66, 0xba800000, v5
	v_mov_b32_e32 v73, v68
	v_add_f32_dpp v0, v0, v0 row_mirror row_mask:0xf bank_mask:0xf bound_ctrl:1
	v_fmamk_f32 v109, v5, 0xba800000, v57
	v_readlane_b32 s2, v0, 16
	v_readlane_b32 s13, v0, 48
	v_readlane_b32 s0, v0, 0
	v_readlane_b32 s1, v0, 32
	v_mov_b32_e32 v0, s2
	v_mov_b32_e32 v1, s13
	v_pk_add_f32 v[0:1], s[0:1], v[0:1]
	v_fmac_f32_e32 v56, 0xba800000, v5
	v_add_f32_e32 v7, v0, v1
	v_mov_b32_e32 v0, v20
	v_mov_b32_e32 v1, v24
	v_pk_fma_f32 v[0:1], v[0:1], v[0:1], v[2:3]
	v_mov_b32_e32 v2, v18
	v_mov_b32_e32 v3, v22
	v_pk_fma_f32 v[0:1], v[2:3], v[2:3], v[0:1]
	v_mov_b32_e32 v2, v19
	v_mov_b32_e32 v3, v23
	v_pk_fma_f32 v[0:1], v[2:3], v[2:3], v[0:1]
	v_pk_mul_f32 v[2:3], v[110:111], v[110:111]
	v_add_f32_e32 v0, v0, v1
	v_pk_fma_f32 v[2:3], v[46:47], v[46:47], v[2:3]
	v_fmamk_f32 v108, v5, 0xba800000, v53
	v_pk_fma_f32 v[2:3], v[42:43], v[42:43], v[2:3]
	v_fmamk_f32 v122, v5, 0xba800000, v71
	v_pk_fma_f32 v[2:3], v[104:105], v[104:105], v[2:3]
	v_fmac_f32_e32 v70, 0xba800000, v5
	v_add_f32_e32 v0, v3, v0
	v_add_f32_e32 v0, v2, v0
	v_pk_mul_f32 v[2:3], v[128:129], v[128:129]
	v_fmamk_f32 v123, v5, 0xba800000, v67
	v_pk_fma_f32 v[2:3], v[72:73], v[72:73], v[2:3]
	v_mov_b32_e32 v71, v66
	v_fmamk_f32 v103, v5, 0xba800000, v55
	v_fmac_f32_e32 v54, 0xba800000, v5
	v_fmamk_f32 v102, v5, 0xba800000, v51
	v_fmac_f32_e32 v50, 0xba800000, v5
	v_fmac_f32_e32 v52, 0xba800000, v5
	v_mov_b32_e32 v53, v56
	v_pk_mul_f32 v[4:5], v[108:109], v[108:109]
	v_pk_fma_f32 v[2:3], v[70:71], v[70:71], v[2:3]
	v_pk_fma_f32 v[4:5], v[52:53], v[52:53], v[4:5]
	v_mov_b32_e32 v51, v54
	v_pk_fma_f32 v[2:3], v[122:123], v[122:123], v[2:3]
	v_pk_fma_f32 v[4:5], v[50:51], v[50:51], v[4:5]
	v_add_f32_e32 v2, v2, v3
	v_pk_fma_f32 v[4:5], v[102:103], v[102:103], v[4:5]
	v_add_f32_dpp v0, v0, v0 quad_perm:[1,0,3,2] row_mask:0xf bank_mask:0xf bound_ctrl:1
	v_add_f32_e32 v2, v5, v2
	v_add_f32_e32 v2, v4, v2
	v_add_f32_dpp v0, v0, v0 quad_perm:[2,3,0,1] row_mask:0xf bank_mask:0xf bound_ctrl:1
	v_fmamk_f32 v130, v6, 0xba800000, v83
	v_add_f32_dpp v2, v2, v2 quad_perm:[1,0,3,2] row_mask:0xf bank_mask:0xf bound_ctrl:1
	v_add_f32_dpp v0, v0, v0 row_half_mirror row_mask:0xf bank_mask:0xf bound_ctrl:1
	v_fmamk_f32 v131, v6, 0xba800000, v77
	v_add_f32_dpp v2, v2, v2 quad_perm:[2,3,0,1] row_mask:0xf bank_mask:0xf bound_ctrl:1
	v_add_f32_dpp v0, v0, v0 row_mirror row_mask:0xf bank_mask:0xf bound_ctrl:1
	v_fmac_f32_e32 v76, 0xba800000, v6
	v_add_f32_dpp v2, v2, v2 row_half_mirror row_mask:0xf bank_mask:0xf bound_ctrl:1
	v_readlane_b32 s2, v0, 16
	v_readlane_b32 s13, v0, 48
	v_add_f32_dpp v2, v2, v2 row_mirror row_mask:0xf bank_mask:0xf bound_ctrl:1
	v_readlane_b32 s0, v0, 0
	v_readlane_b32 s1, v0, 32
	v_mov_b32_e32 v0, s2
	v_mov_b32_e32 v1, s13
	v_readlane_b32 s2, v2, 16
	v_readlane_b32 s13, v2, 48
	v_pk_add_f32 v[0:1], s[0:1], v[0:1]
	v_readlane_b32 s0, v2, 0
	v_readlane_b32 s1, v2, 32
	v_mov_b32_e32 v2, s2
	v_mov_b32_e32 v3, s13
	v_pk_add_f32 v[2:3], s[0:1], v[2:3]
	v_mov_b32_e32 v5, v0
	v_mov_b32_e32 v4, v2
	v_mov_b32_e32 v0, v3
	v_pk_add_f32 v[0:1], v[4:5], v[0:1]
; __device__ __forceinline__ u32x4 pack8(const f32x4 a, const f32x4 b) { u32x4 w; w.x = pk_bf16(a[0], a[1]); w.y = pk_bf16(a[2], a[3]); w.z = pk_bf16(b[0], b[1]); w.w = pk_bf16(b[2], b[3]); return w; }
; __device__ __forceinline__ void phase_ln(const float* RES, const bf16_t* DEL, float* X, bf16_t* XB, const float* g, const float* b, bool write_xb) {
;     ...
;             rs[r] = rsqrtf(wave_sum(q) * (1.f / 1024.f) + 1e-5f); }
; #pragma unroll
;         for (int i = 0; i < 2; ++i) { const int c = i * 512 + lane * 8;
;             const f32x4 ga = *(const f32x4*)(g + c), gb = *(const f32x4*)(g + c + 4), ba = *(const f32x4*)(b + c), bb = *(const f32x4*)(b + c + 4);
; #pragma unroll
;             for (int r = 0; r < 4; ++r) { const size_t ro = (size_t)(base + r * nw) * 1024 + c;
;                 const f32x4 oa = v[r][2 * i] * rs[r] * ga + ba, ob = v[r][2 * i + 1] * rs[r] * gb + bb;
;                 *(f32x4*)(X + ro) = oa; *(f32x4*)(X + ro + 4) = ob;
;                 if (write_xb) *(u32x4*)(XB + ro) = pack8(oa, ob); } }
	v_fmac_f32_e32 v82, 0xba800000, v6
	v_pk_fma_f32 v[132:133], v[0:1], s[50:51], v[182:183] op_sel_hi:[1,0,0]
	v_fmac_f32_e32 v74, 0xba800000, v6
	v_mul_f32_e32 v0, 0x4b800000, v133
	v_cmp_gt_f32_e32 vcc, s8, v133
	v_mov_b32_e32 v83, v76
	v_fmamk_f32 v117, v6, 0xba800000, v65
	v_cndmask_b32_e32 v0, v133, v0, vcc
	v_rsq_f32_e32 v0, v0
	v_fmac_f32_e32 v64, 0xba800000, v6
	v_fmamk_f32 v116, v6, 0xba800000, v61
	v_fmamk_f32 v124, v6, 0xba800000, v79
	v_mul_f32_e32 v1, 0x45800000, v0
	v_cndmask_b32_e32 v118, v0, v1, vcc
	v_pk_mul_f32 v[0:1], v[130:131], v[130:131]
	v_fmac_f32_e32 v78, 0xba800000, v6
	v_pk_fma_f32 v[0:1], v[82:83], v[82:83], v[0:1]
	v_mov_b32_e32 v79, v74
	v_fmac_f32_e32 v62, 0xba800000, v6
	v_fmac_f32_e32 v60, 0xba800000, v6
	v_mov_b32_e32 v61, v64
	v_pk_mul_f32 v[2:3], v[116:117], v[116:117]
	v_fmamk_f32 v125, v6, 0xba800000, v75
	v_pk_fma_f32 v[0:1], v[78:79], v[78:79], v[0:1]
	v_fmamk_f32 v112, v6, 0xba800000, v59
	v_fmac_f32_e32 v58, 0xba800000, v6
	v_pk_fma_f32 v[2:3], v[60:61], v[60:61], v[2:3]
	v_mov_b32_e32 v59, v62
	v_pk_fma_f32 v[0:1], v[124:125], v[124:125], v[0:1]
	v_fmamk_f32 v113, v6, 0xba800000, v63
	v_pk_fma_f32 v[2:3], v[58:59], v[58:59], v[2:3]
	v_add_f32_e32 v0, v0, v1
	v_pk_fma_f32 v[2:3], v[112:113], v[112:113], v[2:3]
	v_fmamk_f32 v126, v7, 0xba800000, v93
	v_add_f32_e32 v0, v3, v0
	v_add_f32_e32 v0, v2, v0
	v_fmamk_f32 v127, v7, 0xba800000, v89
	v_fmac_f32_e32 v88, 0xba800000, v7
	v_add_f32_dpp v0, v0, v0 quad_perm:[1,0,3,2] row_mask:0xf bank_mask:0xf bound_ctrl:1
	v_fmac_f32_e32 v92, 0xba800000, v7
	v_fmac_f32_e32 v86, 0xba800000, v7
	v_add_f32_dpp v0, v0, v0 quad_perm:[2,3,0,1] row_mask:0xf bank_mask:0xf bound_ctrl:1
	v_mov_b32_e32 v93, v88
	v_fmamk_f32 v115, v7, 0xba800000, v101
	v_add_f32_dpp v0, v0, v0 row_half_mirror row_mask:0xf bank_mask:0xf bound_ctrl:1
	v_fmac_f32_e32 v100, 0xba800000, v7
	v_fmamk_f32 v114, v7, 0xba800000, v99
	v_add_f32_dpp v0, v0, v0 row_mirror row_mask:0xf bank_mask:0xf bound_ctrl:1
	v_fmamk_f32 v120, v7, 0xba800000, v91
	v_readlane_b32 s0, v0, 0
	v_readlane_b32 s2, v0, 16
	v_readlane_b32 s1, v0, 32
	v_readlane_b32 s13, v0, 48
	v_pk_mul_f32 v[0:1], v[126:127], v[126:127]
	v_fmac_f32_e32 v90, 0xba800000, v7
	v_pk_fma_f32 v[0:1], v[92:93], v[92:93], v[0:1]
	v_mov_b32_e32 v91, v86
	v_fmac_f32_e32 v96, 0xba800000, v7
	v_fmac_f32_e32 v98, 0xba800000, v7
	v_mov_b32_e32 v99, v100
	v_pk_mul_f32 v[2:3], v[114:115], v[114:115]
	v_fmamk_f32 v121, v7, 0xba800000, v87
	v_pk_fma_f32 v[0:1], v[90:91], v[90:91], v[0:1]
	v_fmamk_f32 v106, v7, 0xba800000, v95
	v_fmac_f32_e32 v94, 0xba800000, v7
	v_pk_fma_f32 v[2:3], v[98:99], v[98:99], v[2:3]
	v_mov_b32_e32 v95, v96
	v_pk_fma_f32 v[0:1], v[120:121], v[120:121], v[0:1]
	v_fmamk_f32 v107, v7, 0xba800000, v97
	v_pk_fma_f32 v[2:3], v[94:95], v[94:95], v[2:3]
	v_add_f32_e32 v0, v0, v1
	v_pk_fma_f32 v[2:3], v[106:107], v[106:107], v[2:3]
	v_pk_mul_f32 v[136:137], v[20:21], v[118:119] op_sel_hi:[1,0]
	v_add_f32_e32 v0, v3, v0
	v_add_f32_e32 v0, v2, v0
	v_pk_mul_f32 v[18:19], v[18:19], v[118:119] op_sel_hi:[1,0]
	v_pk_mul_f32 v[22:23], v[22:23], v[118:119] op_sel_hi:[1,0]
	v_add_f32_dpp v0, v0, v0 quad_perm:[1,0,3,2] row_mask:0xf bank_mask:0xf bound_ctrl:1
	v_cmp_gt_f32_e64 s[36:37], s8, v132
	s_andn2_b64 vcc, exec, s[42:43]
	v_add_f32_dpp v0, v0, v0 quad_perm:[2,3,0,1] row_mask:0xf bank_mask:0xf bound_ctrl:1
	s_nop 1
	v_add_f32_dpp v0, v0, v0 row_half_mirror row_mask:0xf bank_mask:0xf bound_ctrl:1
	s_nop 1
	v_add_f32_dpp v0, v0, v0 row_mirror row_mask:0xf bank_mask:0xf bound_ctrl:1
	s_nop 0
	v_readlane_b32 s46, v0, 0
	v_readlane_b32 s14, v0, 16
	v_readlane_b32 s47, v0, 32
	v_readlane_b32 s15, v0, 48
	global_load_dwordx4 v[0:3], v[30:31], off offset:16
	global_load_dwordx4 v[8:11], v[30:31], off
	global_load_dwordx4 v[4:7], v[32:33], off offset:16
	global_load_dwordx4 v[14:17], v[32:33], off
	global_load_dwordx4 v[138:141], v[32:33], off offset:2048
	global_load_dwordx4 v[142:145], v[30:31], off offset:2048
	global_load_dwordx4 v[146:149], v[30:31], off offset:2064
	global_load_dwordx4 v[150:153], v[32:33], off offset:2064
	s_waitcnt vmcnt(0)
	v_pk_fma_f32 v[20:21], v[18:19], v[10:11], v[16:17]
	v_pk_fma_f32 v[18:19], v[136:137], v[8:9], v[14:15]
	v_pk_mul_f32 v[136:137], v[24:25], v[118:119] op_sel_hi:[1,0]
	v_pk_fma_f32 v[24:25], v[22:23], v[2:3], v[6:7]
	v_pk_fma_f32 v[22:23], v[136:137], v[0:1], v[4:5]
	v_lshl_add_u64 v[136:137], v[134:135], 2, s[68:69]
	global_store_dwordx4 v[136:137], v[18:21], off
	global_store_dwordx4 v[136:137], v[22:25], off offset:16
	s_cbranch_vccnz .LBB0_222
	v_cvt_pk_bf16_f32 v18, v18, v19
	v_cvt_pk_bf16_f32 v19, v20, v21
	v_cvt_pk_bf16_f32 v20, v22, v23
	v_cvt_pk_bf16_f32 v21, v24, v25
	v_lshl_add_u64 v[22:23], v[134:135], 1, s[72:73]
	global_store_dwordx4 v[22:23], v[18:21], off

; __device__ __forceinline__ u32x4 pack8(const f32x4 a, const f32x4 b) { u32x4 w; w.x = pk_bf16(a[0], a[1]); w.y = pk_bf16(a[2], a[3]); w.z = pk_bf16(b[0], b[1]); w.w = pk_bf16(b[2], b[3]); return w; }
; __device__ __forceinline__ void phase_ln(const float* RES, const bf16_t* DEL, float* X, bf16_t* XB, const float* g, const float* b, bool write_xb) {
;     ...
;         for (int i = 0; i < 2; ++i) { const int c = i * 512 + lane * 8;
;             const f32x4 ga = *(const f32x4*)(g + c), gb = *(const f32x4*)(g + c + 4), ba = *(const f32x4*)(b + c), bb = *(const f32x4*)(b + c + 4);
; #pragma unroll
;             for (int r = 0; r < 4; ++r) { const size_t ro = (size_t)(base + r * nw) * 1024 + c;
;                 const f32x4 oa = v[r][2 * i] * rs[r] * ga + ba, ob = v[r][2 * i + 1] * rs[r] * gb + bb;
;                 *(f32x4*)(X + ro) = oa; *(f32x4*)(X + ro + 4) = ob;
;                 if (write_xb) *(u32x4*)(XB + ro) = pack8(oa, ob); } }
.LBB0_228:
	v_mov_b32_e32 v8, v138
	v_mov_b32_e32 v9, v139
	v_mov_b32_e32 v10, v140
	v_mov_b32_e32 v11, v141
	v_mov_b32_e32 v14, v142
	v_mov_b32_e32 v15, v143
	v_mov_b32_e32 v16, v144
	v_mov_b32_e32 v17, v145
	s_nop 0
	v_mov_b32_e32 v0, v146
	v_mov_b32_e32 v1, v147
	v_mov_b32_e32 v2, v148
	v_mov_b32_e32 v3, v149
	v_mov_b32_e32 v4, v150
	v_mov_b32_e32 v5, v151
	v_mov_b32_e32 v6, v152
	v_mov_b32_e32 v7, v153
	v_mov_b32_e32 v49, v111
	v_mov_b32_e32 v47, v110
	v_mov_b32_e32 v119, v118
	v_mov_b32_e32 v18, v118
	v_mov_b32_e32 v19, v118
	v_mov_b32_e32 v45, v105
	v_mov_b32_e32 v43, v104
	v_lshl_add_u64 v[20:21], v[38:39], 0, v[26:27]
	v_pk_mul_f32 v[22:23], v[44:45], v[18:19]
	v_pk_mul_f32 v[44:45], v[48:49], v[118:119]
	v_pk_mul_f32 v[18:19], v[42:43], v[18:19]
	v_pk_mul_f32 v[42:43], v[46:47], v[118:119]
	s_and_b64 vcc, exec, s[38:39]
	v_lshl_add_u64 v[46:47], v[20:21], 2, s[68:69]
	s_movk_i32 s1, 0x7fff
	v_pk_fma_f32 v[24:25], v[22:23], v[16:17], v[10:11]
	v_pk_fma_f32 v[22:23], v[44:45], v[14:15], v[8:9]
	v_pk_fma_f32 v[20:21], v[18:19], v[2:3], v[6:7]
	v_pk_fma_f32 v[18:19], v[42:43], v[0:1], v[4:5]
	global_store_dwordx4 v[46:47], v[22:25], off offset:2048
	global_store_dwordx4 v[46:47], v[18:21], off offset:2064
	s_cbranch_vccnz .LBB0_230
	v_or_b32_e32 v38, v38, v28
	v_cvt_pk_bf16_f32 v22, v22, v23
	v_cvt_pk_bf16_f32 v23, v24, v25
	v_cvt_pk_bf16_f32 v24, v18, v19
	v_cvt_pk_bf16_f32 v25, v20, v21
	v_lshl_add_u64 v[18:19], v[38:39], 1, s[72:73]
	global_store_dwordx4 v[18:19], v[22:25], off

; #define LAS __attribute__((address_space(3)))
; __device__ __forceinline__ int otid() { int t = threadIdx.x; asm volatile("" : "+v"(t)); return t; }
; __device__ __forceinline__ int obid() { int b = blockIdx.x; asm volatile("" : "+s"(b)); return b; }
; __device__ __forceinline__ void phase_attn(const Params& p, int l, LAS unsigned char* ldsb) {
;     unsigned char* R = p.ws + WS_R;
;     const bf16_t* QKV = (const bf16_t*)(R + R_QKV); bf16_t* ATT = (bf16_t*)(R + R_ATT);
;     const float* relb = p.in[7]; const float* sinks = p.in[8] + l * 8;
;     const int tid = otid(), wid = tid >> 6, lane = tid & 63, fr = lane & 15, fq = lane >> 4;
;     LAS bf16_t* Ks = (LAS bf16_t*)ldsb;
;     LAS bf16_t* Vt = (LAS bf16_t*)(ldsb + 36864);
;     LAS float* biasL = (LAS float*)(ldsb + 70656);
;     LAS bf16_t* Pw = (LAS bf16_t*)(ldsb + 72704) + wid * (16 * 168);
;     for (int item = obid(); item < 512; item += gridDim.x) {
;         const int g = item & 1, n = (item >> 1) & 31, b = item >> 6;
;         const long tokc = (long)b * SEQ + n * 128, tokp = tokc - 128;
;         for (int idx = tid; idx < 2048; idx += 512) {
;             const int key = idx >> 3, d8 = idx & 7; u32x4 v = (u32x4){0u, 0u, 0u, 0u}, kv = (u32x4){0u, 0u, 0u, 0u};
;             if (n > 0 || key >= 128) { const bf16_t* src = QKV + (size_t)(tokp + key) * 768 + 512 + g * 64 + d8 * 8; kv = *(const u32x4*)src; v = *(const u32x4*)(src + 128); }
;             *(LAS u32x4*)(Ks + key * 72 + d8 * 8) = kv;
; #pragma unroll
;             for (int e = 0; e < 8; ++e) Vt[(d8 * 8 + e) * 264 + key] = (bf16_t)((e & 1) ? (v[e >> 1] >> 16) : (v[e >> 1] & 0xffffu));
;         }
;         { const int hl = tid >> 7, d = tid & 127; int bk = d;
;           if (d >= 16) { bk = 16 + (int)(__logf((float)d * 0.0625f) * (16.f / 2.07944154168f)); bk = bk > 31 ? 31 : bk; }
;           biasL[tid] = relb[bk * 8 + g * 4 + hl]; }
;         __syncthreads();
;         const int hl = wid >> 1, hq = g * 4 + hl; const float sink = sinks[hq];
;         for (int rt = 0; rt < 4; ++rt) {
;             const int q0 = (wid & 1) * 64 + rt * 16, kstart = q0 < 96 ? q0 : 96;
;             bf16x8 qa0, qa1; { const bf16_t* qp = QKV + (size_t)(tokc + q0 + fr) * 768 + hq * 64 + fq * 8; qa0 = *(const bf16x8*)qp; qa1 = *(const bf16x8*)(qp + 32); }
.Lat_entry:
	v_and_b32_e32 v0, 63, v183
	v_and_b32_e32 v1, 15, v183
	v_bfe_u32 v2, v183, 4, 2
	v_lshrrev_b32_e32 v4, 6, v183
	s_nop 0
	v_readfirstlane_b32 s44, v4
	s_nop 0
	s_lshr_b32 s45, s44, 1
	s_and_b32 s46, s44, 1
	v_readlane_b32 s0, v252, 0
	v_readlane_b32 s1, v252, 1
	s_sub_u32 s0, s0, 0xe0
	s_subb_u32 s1, s1, 0
	s_load_dwordx2 s[14:15], s[0:1], 0x38
	s_load_dwordx2 s[26:27], s[0:1], 0x40
	v_readlane_b32 s85, v243, 45
	s_nop 0
	s_lshr_b32 s85, s85, 1
	s_mov_b32 s82, 0x3e38aa3b
	v_mov_b32_e32 v38, s82
	v_mov_b32_e32 v39, s82
	v_lshrrev_b32_e32 v4, 3, v183
	v_and_b32_e32 v5, 7, v183
	v_mul_u32_u24_e32 v7, 1536, v4
	v_lshl_add_u32 v7, v5, 4, v7
	v_and_b32_e32 v6, 7, v4
	v_xor_b32_e32 v6, v6, v5
	v_lshlrev_b32_e32 v6, 4, v6
	v_lshl_add_u32 v6, v4, 7, v6
	v_bfe_u32 v3, v4, 1, 3
	v_xor_b32_e32 v3, v3, v5
	v_lshlrev_b32_e32 v3, 4, v3
	v_lshl_add_u32 v3, v4, 7, v3
	v_and_b32_e32 v8, 127, v183
	v_lshrrev_b32_e32 v4, 7, v183
	v_cvt_f32_u32_e32 v5, v8
	v_mul_f32_e32 v5, 0x3d800000, v5
	v_max_f32_e32 v5, 1.0, v5
	v_log_f32_e32 v5, v5
	s_nop 0
	v_mul_f32_e32 v5, 0x40aaaaab, v5
	v_cvt_i32_f32_e32 v5, v5
	v_add_u32_e32 v5, 16, v5
	v_min_u32_e32 v5, 31, v5
	v_cmp_gt_u32_e32 vcc, 16, v8
	s_nop 1
	v_cndmask_b32_e32 v10, v5, v8, vcc
	v_lshlrev_b32_e32 v10, 5, v10
	v_lshl_add_u32 v10, v4, 2, v10
	v_mul_u32_u24_e32 v9, 3328, v4
	v_sub_u32_e32 v5, 160, v8
	v_lshl_add_u32 v9, v5, 2, v9
	v_add_u32_e32 v9, 131072, v9
	v_add_u32_e32 v5, 96, v8
	v_subrev_u32_e32 v29, 32, v8
	v_cmp_gt_u32_e32 vcc, 32, v8
	s_nop 1
	v_cndmask_b32_e32 v5, v5, v29, vcc
	v_sub_u32_e32 v5, 160, v5
	v_mul_u32_u24_e32 v11, 3328, v4
	v_lshl_add_u32 v11, v5, 2, v11
	v_add_u32_e32 v11, 131072, v11
	v_lshlrev_b32_e32 v5, 2, v183
	v_add_u32_e32 v5, 144384, v5
	v_cmp_gt_u32_e32 vcc, 65, v8
	s_nop 1
	v_cndmask_b32_e32 v11, v5, v11, vcc
	v_bfe_u32 v4, v1, 1, 3
	v_xor_b32_e32 v4, v4, v2
	v_lshlrev_b32_e32 v4, 4, v4
	v_lshl_add_u32 v13, v1, 7, v4
	v_xor_b32_e32 v14, 64, v13
	v_and_b32_e32 v4, 3, v1
	v_mul_u32_u24_e32 v17, 832, v4
	v_and_b32_e32 v4, 12, v1
	v_lshlrev_b32_e32 v4, 2, v4
	v_sub_u32_e32 v17, v17, v4
	v_lshl_add_u32 v17, v2, 4, v17
	s_mul_i32 s51, s45, 3328
	s_add_u32 s51, s51, 131072
	v_add_u32_e32 v17, s51, v17
	v_lshrrev_b32_e32 v4, 2, v1
	v_lshl_add_u32 v4, v2, 2, v4
	v_and_b32_e32 v5, 7, v4
	v_bfe_u32 v29, v1, 1, 1
	v_and_b32_e32 v30, 1, v1
	v_lshlrev_b32_e32 v30, 3, v30
	v_lshl_add_u32 v30, v4, 7, v30
	v_add_u32_e32 v30, 32768, v30
	v_or_b32_e32 v4, 0, v29
	v_xor_b32_e32 v4, v4, v5
	v_lshl_add_u32 v19, v4, 4, v30
	v_or_b32_e32 v4, 2, v29
	v_xor_b32_e32 v4, v4, v5
	v_lshl_add_u32 v20, v4, 4, v30
	v_or_b32_e32 v4, 4, v29
	v_xor_b32_e32 v4, v4, v5
	v_lshl_add_u32 v21, v4, 4, v30
	v_or_b32_e32 v4, 6, v29
	v_xor_b32_e32 v4, v4, v5
	v_lshl_add_u32 v22, v4, 4, v30
	v_mul_u32_u24_e32 v27, 1536, v1
	v_lshl_add_u32 v27, v2, 4, v27
	v_lshlrev_b32_e32 v28, 10, v1
	v_lshl_add_u32 v28, v2, 3, v28
	v_xor_b32_e32 v29, 16, v0
	v_lshlrev_b32_e32 v29, 2, v29
	v_xor_b32_e32 v30, 32, v0
	v_lshlrev_b32_e32 v30, 2, v30
	s_and_b32 s2, s5, 1
	s_lshr_b32 s13, s5, 1
	s_and_b32 s13, s13, 31
	s_lshr_b32 s25, s5, 6
	s_lshl_b32 s32, s25, 12
	s_lshl_b32 s51, s13, 7
	s_add_u32 s32, s32, s51
	s_lshl_b32 s47, s2, 2
	s_add_u32 s47, s47, s45
	s_waitcnt lgkmcnt(0)
	s_lshl_b32 s51, s2, 4
	v_add_u32_e32 v4, s51, v10
	global_load_dword v33, v4, s[14:15]
	s_lshl_b32 s51, s85, 3
	s_add_u32 s51, s51, s47
	s_lshl_b32 s51, s51, 2
	s_add_u32 s36, s26, s51
	s_addc_u32 s37, s27, 0
	s_load_dword s83, s[36:37], 0x0
	s_mul_i32 s51, s32, 1536
	s_lshl_b32 s81, s2, 7
	s_add_u32 s51, s51, s81
	s_add_u32 s51, s51, 1024
	s_add_u32 s36, s74, s51
	s_addc_u32 s37, s75, 0
	s_add_u32 s38, s36, 25165824
	s_addc_u32 s39, s37, 0
	v_add_u32_e32 v15, 65536, v3
	v_add_u32_e32 v16, 65536, v6
	s_cmp_eq_u32 s13, 0
	s_nop 0
	s_cbranch_scc1 .Lat_stage_n0
	s_sub_u32 s36, s36, 196608
	s_subb_u32 s37, s37, 0
	s_sub_u32 s38, s38, 196608
	s_subb_u32 s39, s39, 0
	global_load_dwordx4 v[72:75], v7, s[36:37]
	global_load_dwordx4 v[76:79], v7, s[36:37] offset:256
	s_add_u32 s36, s36, 98304
	s_addc_u32 s37, s37, 0
	global_load_dwordx4 v[80:83], v7, s[38:39]
	global_load_dwordx4 v[84:87], v7, s[38:39] offset:256
	s_add_u32 s38, s38, 98304
	s_addc_u32 s39, s39, 0
	global_load_dwordx4 v[88:91], v7, s[36:37]
	global_load_dwordx4 v[92:95], v7, s[36:37] offset:256
	s_add_u32 s36, s36, 98304
	s_addc_u32 s37, s37, 0
	global_load_dwordx4 v[96:99], v7, s[38:39]
	global_load_dwordx4 v[100:103], v7, s[38:39] offset:256
	s_add_u32 s38, s38, 98304
	s_addc_u32 s39, s39, 0
	global_load_dwordx4 v[104:107], v7, s[36:37]
	global_load_dwordx4 v[108:111], v7, s[36:37] offset:256
	s_add_u32 s36, s36, 98304
	s_addc_u32 s37, s37, 0
	global_load_dwordx4 v[112:115], v7, s[38:39]
	global_load_dwordx4 v[116:119], v7, s[38:39] offset:256
	s_add_u32 s38, s38, 98304
	s_addc_u32 s39, s39, 0
	global_load_dwordx4 v[120:123], v7, s[36:37]
	global_load_dwordx4 v[124:127], v7, s[36:37] offset:256
	global_load_dwordx4 v[128:131], v7, s[38:39]
	global_load_dwordx4 v[132:135], v7, s[38:39] offset:256
	s_mov_b32 s51, 0
	s_lshr_b32 s81, s51, 2
	s_lshl_b32 s81, s81, 14
	s_and_b32 s51, s51, 3
	s_lshl_b32 s51, s51, 4
	s_add_u32 s81, s81, s51
	s_lshl_b32 s51, s46, 6
	s_add_u32 s81, s81, s51
	s_add_u32 s81, s81, s32
	s_mul_i32 s81, s81, 1536
	s_lshl_b32 s51, s47, 7
	s_add_u32 s81, s81, s51
	s_add_u32 s40, s74, s81
	s_addc_u32 s41, s75, 0
	global_load_dwordx4 v[48:51], v27, s[40:41]
	global_load_dwordx4 v[52:55], v27, s[40:41] offset:64
	s_waitcnt vmcnt(18)
	v_mul_f32_e32 v33, 0x3fb8aa3b, v33
	v_mov_b32_e32 v34, 0xff800000
	ds_write_b32 v9, v33 offset:0
	ds_write_b32 v11, v34 offset:0
	ds_write_b32 v9, v33 offset:836
	ds_write_b32 v11, v34 offset:836
	ds_write_b32 v9, v33 offset:1672
	ds_write_b32 v11, v34 offset:1672
	ds_write_b32 v9, v33 offset:2508
	ds_write_b32 v11, v34 offset:2508
	s_waitcnt vmcnt(16)
	ds_write_b128 v3, v[72:75] offset:0
	ds_write_b128 v6, v[76:79] offset:32768
	s_waitcnt vmcnt(14)
	ds_write_b128 v15, v[80:83] offset:0
	ds_write_b128 v16, v[84:87] offset:32768
	s_waitcnt vmcnt(12)
	ds_write_b128 v3, v[88:91] offset:8192
	ds_write_b128 v6, v[92:95] offset:40960
	s_waitcnt vmcnt(10)
	ds_write_b128 v15, v[96:99] offset:8192
	ds_write_b128 v16, v[100:103] offset:40960
	s_waitcnt vmcnt(8)
	ds_write_b128 v3, v[104:107] offset:16384
	ds_write_b128 v6, v[108:111] offset:49152
	s_waitcnt vmcnt(6)
	ds_write_b128 v15, v[112:115] offset:16384
	ds_write_b128 v16, v[116:119] offset:49152
	s_waitcnt vmcnt(4)
	ds_write_b128 v3, v[120:123] offset:24576
	ds_write_b128 v6, v[124:127] offset:57344
	s_waitcnt vmcnt(2)
	ds_write_b128 v15, v[128:131] offset:24576
	ds_write_b128 v16, v[132:135] offset:57344
	s_branch .Lat_staged
; #define LAS __attribute__((address_space(3)))
; __device__ __forceinline__ void phase_attn(const Params& p, int l, LAS unsigned char* ldsb) {
;     ...
;         for (int idx = tid; idx < 2048; idx += 512) {
;             const int key = idx >> 3, d8 = idx & 7; u32x4 v = (u32x4){0u, 0u, 0u, 0u}, kv = (u32x4){0u, 0u, 0u, 0u};
;             if (n > 0 || key >= 128) { const bf16_t* src = QKV + (size_t)(tokp + key) * 768 + 512 + g * 64 + d8 * 8; kv = *(const u32x4*)src; v = *(const u32x4*)(src + 128); }
;             *(LAS u32x4*)(Ks + key * 72 + d8 * 8) = kv;
; #pragma unroll
;             for (int e = 0; e < 8; ++e) Vt[(d8 * 8 + e) * 264 + key] = (bf16_t)((e & 1) ? (v[e >> 1] >> 16) : (v[e >> 1] & 0xffffu));
;         }
;         { const int hl = tid >> 7, d = tid & 127; int bk = d;
;           if (d >= 16) { bk = 16 + (int)(__logf((float)d * 0.0625f) * (16.f / 2.07944154168f)); bk = bk > 31 ? 31 : bk; }
;           biasL[tid] = relb[bk * 8 + g * 4 + hl]; }
;         __syncthreads();
.Lat_stage_n0:
	global_load_dwordx4 v[104:107], v7, s[36:37]
	global_load_dwordx4 v[108:111], v7, s[36:37] offset:256
	s_add_u32 s36, s36, 98304
	s_addc_u32 s37, s37, 0
	global_load_dwordx4 v[112:115], v7, s[38:39]
	global_load_dwordx4 v[116:119], v7, s[38:39] offset:256
	s_add_u32 s38, s38, 98304
	s_addc_u32 s39, s39, 0
	global_load_dwordx4 v[120:123], v7, s[36:37]
	global_load_dwordx4 v[124:127], v7, s[36:37] offset:256
	global_load_dwordx4 v[128:131], v7, s[38:39]
	global_load_dwordx4 v[132:135], v7, s[38:39] offset:256
	s_mov_b32 s51, 0
	s_lshr_b32 s81, s51, 2
	s_lshl_b32 s81, s81, 14
	s_and_b32 s51, s51, 3
	s_lshl_b32 s51, s51, 4
	s_add_u32 s81, s81, s51
	s_lshl_b32 s51, s46, 6
	s_add_u32 s81, s81, s51
	s_add_u32 s81, s81, s32
	s_mul_i32 s81, s81, 1536
	s_lshl_b32 s51, s47, 7
	s_add_u32 s81, s81, s51
	s_add_u32 s40, s74, s81
	s_addc_u32 s41, s75, 0
	global_load_dwordx4 v[48:51], v27, s[40:41]
	global_load_dwordx4 v[52:55], v27, s[40:41] offset:64
	v_mov_b32_e32 v72, 0
	v_mov_b32_e32 v73, 0
	v_mov_b32_e32 v74, 0
	v_mov_b32_e32 v75, 0
	ds_write_b128 v3, v[72:75] offset:0
	ds_write_b128 v6, v[72:75] offset:32768
	ds_write_b128 v15, v[72:75] offset:0
	ds_write_b128 v16, v[72:75] offset:32768
	ds_write_b128 v3, v[72:75] offset:8192
	ds_write_b128 v6, v[72:75] offset:40960
	ds_write_b128 v15, v[72:75] offset:8192
	ds_write_b128 v16, v[72:75] offset:40960
	s_waitcnt vmcnt(10)
	v_mul_f32_e32 v33, 0x3fb8aa3b, v33
	v_mov_b32_e32 v34, 0xff800000
	ds_write_b32 v9, v33 offset:0
	ds_write_b32 v11, v34 offset:0
	ds_write_b32 v9, v33 offset:836
	ds_write_b32 v11, v34 offset:836
	ds_write_b32 v9, v33 offset:1672
	ds_write_b32 v11, v34 offset:1672
	ds_write_b32 v9, v33 offset:2508
	ds_write_b32 v11, v34 offset:2508
	s_waitcnt vmcnt(8)
	ds_write_b128 v3, v[104:107] offset:16384
	ds_write_b128 v6, v[108:111] offset:49152
	s_waitcnt vmcnt(6)
	ds_write_b128 v15, v[112:115] offset:16384
	ds_write_b128 v16, v[116:119] offset:49152
	s_waitcnt vmcnt(4)
	ds_write_b128 v3, v[120:123] offset:24576
	ds_write_b128 v6, v[124:127] offset:57344
	s_waitcnt vmcnt(2)
	ds_write_b128 v15, v[128:131] offset:24576
	ds_write_b128 v16, v[132:135] offset:57344

; #define LAS __attribute__((address_space(3)))
; __device__ __forceinline__ void phase_attn(const Params& p, int l, LAS unsigned char* ldsb) {
;     ...
;         for (int rt = 0; rt < 4; ++rt) {
;             const int q0 = (wid & 1) * 64 + rt * 16, kstart = q0 < 96 ? q0 : 96;
;             bf16x8 qa0, qa1; { const bf16_t* qp = QKV + (size_t)(tokc + q0 + fr) * 768 + hq * 64 + fq * 8; qa0 = *(const bf16x8*)qp; qa1 = *(const bf16x8*)(qp + 32); }
;             f32x4 S[10];
; #pragma unroll
;             for (int kt = 0; kt < 10; ++kt) {
;                 LAS const bf16_t* kp = Ks + (kstart + kt * 16 + fr) * 72 + fq * 8;
;                 const bf16x8 k0 = *(LAS const bf16x8*)kp, k1 = *(LAS const bf16x8*)(kp + 32);
;                 f32x4 z = (f32x4){0.f, 0.f, 0.f, 0.f};
;                 z = __builtin_amdgcn_mfma_f32_16x16x32_bf16(qa0, k0, z, 0, 0, 0);
;                 z = __builtin_amdgcn_mfma_f32_16x16x32_bf16(qa1, k1, z, 0, 0, 0);
;                 S[kt] = z;
;             }
;             float mx[4] = {-INFINITY, -INFINITY, -INFINITY, -INFINITY};
; #pragma unroll
;             for (int kt = 0; kt < 10; ++kt)
; #pragma unroll
;                 for (int j = 0; j < 4; ++j) {
;                     const int key = kstart + kt * 16 + fr, dist = q0 + 4 * fq + j + 128 - key;
;                     const bool ok = (dist >= 0) && (dist < 128) && (n > 0 || key >= 128);
;                     const float s = ok ? (S[kt][j] * 0.125f + biasL[hl * 128 + (dist & 127)]) : -INFINITY;
;                     S[kt][j] = s; mx[j] = fmaxf(mx[j], s);
;                 }
.Lat_rt:
	s_barrier
	s_and_b32 s51, s48, 3
	s_lshl_b32 s51, s51, 4
	s_lshl_b32 s49, s46, 6
	s_add_u32 s49, s49, s51
	s_min_u32 s50, s49, 96
	s_lshr_b32 s51, s48, 2
	s_lshl_b32 s81, s51, 14
	s_add_u32 s81, s81, s32
	s_add_u32 s81, s81, s49
	s_lshl_b32 s81, s81, 10
	s_lshl_b32 s84, s47, 7
	s_add_u32 s81, s81, s84
	s_add_u32 s81, s81, 0x7000000
	s_add_u32 s42, s74, s81
	s_addc_u32 s43, s75, 0
	s_lshl_b32 s51, s51, 16
	s_lshl_b32 s81, s50, 7
	s_add_u32 s51, s51, s81
	v_add_u32_e32 v15, s51, v13
	v_add_u32_e32 v16, s51, v14
	v_add_u32_e32 v23, s51, v19
	v_add_u32_e32 v24, s51, v20
	v_add_u32_e32 v25, s51, v21
	v_add_u32_e32 v26, s51, v22
	s_sub_u32 s81, s49, s50
	s_sub_u32 s81, 32, s81
	s_lshl_b32 s81, s81, 2
	v_add_u32_e32 v18, s81, v17
	s_sub_u32 s84, 128, s50
	s_lshr_b32 s84, s84, 4
	s_cmp_eq_u32 s13, 0
	s_cselect_b32 s84, s84, 0
	ds_read_b128 v[112:115], v18 offset:0
	ds_read_b128 v[116:119], v18 offset:64
	ds_read_b128 v[120:123], v18 offset:128
	ds_read_b128 v[124:127], v18 offset:192
	ds_read_b128 v[128:131], v18 offset:256
	ds_read_b128 v[132:135], v18 offset:320
	ds_read_b128 v[136:139], v18 offset:384
	ds_read_b128 v[140:143], v18 offset:448
	ds_read_b128 v[144:147], v18 offset:512
	ds_read_b128 v[148:151], v18 offset:576
	ds_read_b128 v[56:59], v15 offset:0
	ds_read_b128 v[60:63], v16 offset:0
	ds_read_b128 v[64:67], v15 offset:2048
	ds_read_b128 v[68:71], v16 offset:2048
	s_waitcnt lgkmcnt(2)
	v_mfma_f32_16x16x32_bf16 v[72:75], v[56:59], v[48:51], 0
	v_mfma_f32_16x16x32_bf16 v[72:75], v[60:63], v[52:55], v[72:75]
	ds_read_b128 v[56:59], v15 offset:4096
	ds_read_b128 v[60:63], v16 offset:4096
	s_waitcnt lgkmcnt(2)
	v_mfma_f32_16x16x32_bf16 v[76:79], v[64:67], v[48:51], 0
	v_mfma_f32_16x16x32_bf16 v[76:79], v[68:71], v[52:55], v[76:79]
	ds_read_b128 v[64:67], v15 offset:6144
	ds_read_b128 v[68:71], v16 offset:6144
	s_waitcnt lgkmcnt(2)
	v_mfma_f32_16x16x32_bf16 v[80:83], v[56:59], v[48:51], 0
	v_mfma_f32_16x16x32_bf16 v[80:83], v[60:63], v[52:55], v[80:83]
	ds_read_b128 v[56:59], v15 offset:8192
	ds_read_b128 v[60:63], v16 offset:8192
	s_waitcnt lgkmcnt(2)
	v_mfma_f32_16x16x32_bf16 v[84:87], v[64:67], v[48:51], 0
	v_mfma_f32_16x16x32_bf16 v[84:87], v[68:71], v[52:55], v[84:87]
	ds_read_b128 v[64:67], v15 offset:10240
	ds_read_b128 v[68:71], v16 offset:10240
	s_waitcnt lgkmcnt(2)
	v_mfma_f32_16x16x32_bf16 v[88:91], v[56:59], v[48:51], 0
	v_mfma_f32_16x16x32_bf16 v[88:91], v[60:63], v[52:55], v[88:91]
	ds_read_b128 v[56:59], v15 offset:12288
	ds_read_b128 v[60:63], v16 offset:12288
	s_waitcnt lgkmcnt(2)
	v_mfma_f32_16x16x32_bf16 v[92:95], v[64:67], v[48:51], 0
	v_mfma_f32_16x16x32_bf16 v[92:95], v[68:71], v[52:55], v[92:95]
	ds_read_b128 v[64:67], v15 offset:14336
	ds_read_b128 v[68:71], v16 offset:14336
	s_waitcnt lgkmcnt(2)
	v_mfma_f32_16x16x32_bf16 v[96:99], v[56:59], v[48:51], 0
	v_mfma_f32_16x16x32_bf16 v[96:99], v[60:63], v[52:55], v[96:99]
	ds_read_b128 v[56:59], v15 offset:16384
	ds_read_b128 v[60:63], v16 offset:16384
	s_waitcnt lgkmcnt(2)
	v_mfma_f32_16x16x32_bf16 v[100:103], v[64:67], v[48:51], 0
	v_mfma_f32_16x16x32_bf16 v[100:103], v[68:71], v[52:55], v[100:103]
	ds_read_b128 v[64:67], v15 offset:18432
	ds_read_b128 v[68:71], v16 offset:18432
	s_waitcnt lgkmcnt(2)
	v_mfma_f32_16x16x32_bf16 v[104:107], v[56:59], v[48:51], 0
	v_mfma_f32_16x16x32_bf16 v[104:107], v[60:63], v[52:55], v[104:107]
	s_waitcnt lgkmcnt(0)
	v_mfma_f32_16x16x32_bf16 v[108:111], v[64:67], v[48:51], 0
	v_mfma_f32_16x16x32_bf16 v[108:111], v[68:71], v[52:55], v[108:111]
	s_add_u32 s51, s48, 1
	s_min_u32 s51, s51, 7
	s_lshr_b32 s81, s51, 2
	s_lshl_b32 s81, s81, 14
	s_and_b32 s51, s51, 3
	s_lshl_b32 s51, s51, 4
	s_add_u32 s81, s81, s51
	s_lshl_b32 s51, s46, 6
	s_add_u32 s81, s81, s51
	s_add_u32 s81, s81, s32
	s_mul_i32 s81, s81, 1536
	s_lshl_b32 s51, s47, 7
	s_add_u32 s81, s81, s51
	s_add_u32 s40, s74, s81
	s_addc_u32 s41, s75, 0
	global_load_dwordx4 v[48:51], v27, s[40:41]
	global_load_dwordx4 v[52:55], v27, s[40:41] offset:64
	v_pk_fma_f32 v[72:73], v[72:73], v[38:39], v[112:113]
	v_pk_fma_f32 v[74:75], v[74:75], v[38:39], v[114:115]
	v_pk_fma_f32 v[76:77], v[76:77], v[38:39], v[116:117]
	v_pk_fma_f32 v[78:79], v[78:79], v[38:39], v[118:119]
	v_pk_fma_f32 v[80:81], v[80:81], v[38:39], v[120:121]
	v_pk_fma_f32 v[82:83], v[82:83], v[38:39], v[122:123]
	v_pk_fma_f32 v[84:85], v[84:85], v[38:39], v[124:125]
	v_pk_fma_f32 v[86:87], v[86:87], v[38:39], v[126:127]
	v_pk_fma_f32 v[88:89], v[88:89], v[38:39], v[128:129]
	v_pk_fma_f32 v[90:91], v[90:91], v[38:39], v[130:131]
	v_pk_fma_f32 v[92:93], v[92:93], v[38:39], v[132:133]
	v_pk_fma_f32 v[94:95], v[94:95], v[38:39], v[134:135]
	v_pk_fma_f32 v[96:97], v[96:97], v[38:39], v[136:137]
	v_pk_fma_f32 v[98:99], v[98:99], v[38:39], v[138:139]
	v_pk_fma_f32 v[100:101], v[100:101], v[38:39], v[140:141]
	v_pk_fma_f32 v[102:103], v[102:103], v[38:39], v[142:143]
	v_pk_fma_f32 v[104:105], v[104:105], v[38:39], v[144:145]
	v_pk_fma_f32 v[106:107], v[106:107], v[38:39], v[146:147]
	v_pk_fma_f32 v[108:109], v[108:109], v[38:39], v[148:149]
	v_pk_fma_f32 v[110:111], v[110:111], v[38:39], v[150:151]
	s_cmp_eq_u32 s84, 0
	s_nop 0
	s_cbranch_scc1 .Lat_nomask
	s_cmp_gt_u32 s84, 0
	s_cselect_b32 s86, 0xff800000, 0
	v_add_f32_e32 v72, s86, v72
	v_add_f32_e32 v73, s86, v73
	v_add_f32_e32 v74, s86, v74
	v_add_f32_e32 v75, s86, v75
	s_cmp_gt_u32 s84, 1
	s_cselect_b32 s86, 0xff800000, 0
	v_add_f32_e32 v76, s86, v76
	v_add_f32_e32 v77, s86, v77
	v_add_f32_e32 v78, s86, v78
	v_add_f32_e32 v79, s86, v79
	s_cmp_gt_u32 s84, 2
	s_cselect_b32 s86, 0xff800000, 0
	v_add_f32_e32 v80, s86, v80
	v_add_f32_e32 v81, s86, v81
	v_add_f32_e32 v82, s86, v82
	v_add_f32_e32 v83, s86, v83
	s_cmp_gt_u32 s84, 3
	s_cselect_b32 s86, 0xff800000, 0
	v_add_f32_e32 v84, s86, v84
	v_add_f32_e32 v85, s86, v85
	v_add_f32_e32 v86, s86, v86
	v_add_f32_e32 v87, s86, v87
	s_cmp_gt_u32 s84, 4
	s_cselect_b32 s86, 0xff800000, 0
	v_add_f32_e32 v88, s86, v88
	v_add_f32_e32 v89, s86, v89
	v_add_f32_e32 v90, s86, v90
	v_add_f32_e32 v91, s86, v91
	s_cmp_gt_u32 s84, 5
	s_cselect_b32 s86, 0xff800000, 0
	v_add_f32_e32 v92, s86, v92
	v_add_f32_e32 v93, s86, v93
	v_add_f32_e32 v94, s86, v94
	v_add_f32_e32 v95, s86, v95
	s_cmp_gt_u32 s84, 6
	s_cselect_b32 s86, 0xff800000, 0
	v_add_f32_e32 v96, s86, v96
	v_add_f32_e32 v97, s86, v97
	v_add_f32_e32 v98, s86, v98
	v_add_f32_e32 v99, s86, v99
	s_cmp_gt_u32 s84, 7
	s_cselect_b32 s86, 0xff800000, 0
	v_add_f32_e32 v100, s86, v100
	v_add_f32_e32 v101, s86, v101
	v_add_f32_e32 v102, s86, v102
	v_add_f32_e32 v103, s86, v103
	s_nop 1
; __device__ __forceinline__ unsigned pk_bf16(float lo, float hi) { const f32x2_t f = {lo, hi}; return __builtin_bit_cast(unsigned, __builtin_convertvector(f, bf16x2_t)); }
; __device__ __forceinline__ void phase_attn(const Params& p, int l, LAS unsigned char* ldsb) {
;     ...
;             float mx[4] = {-INFINITY, -INFINITY, -INFINITY, -INFINITY};
; #pragma unroll
;             for (int kt = 0; kt < 10; ++kt)
; #pragma unroll
;                 for (int j = 0; j < 4; ++j) {
;                     const int key = kstart + kt * 16 + fr, dist = q0 + 4 * fq + j + 128 - key;
;                     const bool ok = (dist >= 0) && (dist < 128) && (n > 0 || key >= 128);
;                     const float s = ok ? (S[kt][j] * 0.125f + biasL[hl * 128 + (dist & 127)]) : -INFINITY;
;                     S[kt][j] = s; mx[j] = fmaxf(mx[j], s);
;                 }
;             float inv[4];
; #pragma unroll
;             for (int j = 0; j < 4; ++j) mx[j] = fmaxf(row16_max(mx[j]), sink);
;             float sm[4] = {0.f, 0.f, 0.f, 0.f};
; #pragma unroll
;             for (int kt = 0; kt < 10; ++kt)
; #pragma unroll
;                 for (int j = 0; j < 4; ++j) { const float e = __expf(S[kt][j] - mx[j]); S[kt][j] = e; sm[j] += e; }
; #pragma unroll
;             for (int j = 0; j < 4; ++j) inv[j] = 1.f / (row16_sum(sm[j]) + __expf(sink - mx[j]));
; #pragma unroll
;             for (int kt = 0; kt < 10; ++kt)
; #pragma unroll
;                 for (int j = 0; j < 4; ++j) Pw[(4 * fq + j) * 168 + kt * 16 + fr] = (bf16_t)(pk_bf16(S[kt][j] * inv[j], 0.f) & 0xffffu);
.Lat_nomask:
	v_max3_f32 v31, v72, v73, v74
	v_max3_f32 v31, v31, v75, v76
	v_max3_f32 v31, v31, v77, v78
	v_max3_f32 v31, v31, v79, v80
	v_max3_f32 v31, v31, v81, v82
	v_max3_f32 v31, v31, v83, v84
	v_max3_f32 v31, v31, v85, v86
	v_max3_f32 v31, v31, v87, v88
	v_max3_f32 v31, v31, v89, v90
	v_max3_f32 v31, v31, v91, v92
	v_max3_f32 v31, v31, v93, v94
	v_max3_f32 v31, v31, v95, v96
	v_max3_f32 v31, v31, v97, v98
	v_max3_f32 v31, v31, v99, v100
	v_max3_f32 v31, v31, v101, v102
	v_max3_f32 v31, v31, v103, v104
	v_max3_f32 v31, v31, v105, v106
	v_max3_f32 v31, v31, v107, v108
	v_max3_f32 v31, v31, v109, v110
	v_max_f32_e32 v31, v31, v111
	v_mov_b32_e32 v33, v31
	s_nop 1
	v_permlane16_swap_b32_e32 v31, v33
	s_nop 1
	v_max_f32_e32 v31, v31, v33
	v_mov_b32_e32 v33, v31
	s_nop 1
	v_permlane32_swap_b32_e32 v31, v33
	s_nop 1
	v_max_f32_e32 v31, v31, v33
	v_max_f32_e32 v31, s83, v31
	v_sub_f32_e32 v40, 0, v31
	v_mov_b32_e32 v41, v40
	v_pk_add_f32 v[72:73], v[72:73], v[40:41]
	v_pk_add_f32 v[74:75], v[74:75], v[40:41]
	v_pk_add_f32 v[76:77], v[76:77], v[40:41]
	v_pk_add_f32 v[78:79], v[78:79], v[40:41]
	v_pk_add_f32 v[80:81], v[80:81], v[40:41]
	v_pk_add_f32 v[82:83], v[82:83], v[40:41]
	v_pk_add_f32 v[84:85], v[84:85], v[40:41]
	v_pk_add_f32 v[86:87], v[86:87], v[40:41]
	v_pk_add_f32 v[88:89], v[88:89], v[40:41]
	v_pk_add_f32 v[90:91], v[90:91], v[40:41]
	v_pk_add_f32 v[92:93], v[92:93], v[40:41]
	v_pk_add_f32 v[94:95], v[94:95], v[40:41]
	v_pk_add_f32 v[96:97], v[96:97], v[40:41]
	v_pk_add_f32 v[98:99], v[98:99], v[40:41]
	v_pk_add_f32 v[100:101], v[100:101], v[40:41]
	v_pk_add_f32 v[102:103], v[102:103], v[40:41]
	v_pk_add_f32 v[104:105], v[104:105], v[40:41]
	v_pk_add_f32 v[106:107], v[106:107], v[40:41]
	v_pk_add_f32 v[108:109], v[108:109], v[40:41]
	v_pk_add_f32 v[110:111], v[110:111], v[40:41]
	v_exp_f32_e32 v72, v72
	v_exp_f32_e32 v73, v73
	v_exp_f32_e32 v74, v74
	v_exp_f32_e32 v75, v75
	v_exp_f32_e32 v76, v76
	v_exp_f32_e32 v77, v77
	v_exp_f32_e32 v78, v78
	v_exp_f32_e32 v79, v79
	v_exp_f32_e32 v80, v80
	v_exp_f32_e32 v81, v81
	v_exp_f32_e32 v82, v82
	v_exp_f32_e32 v83, v83
	v_exp_f32_e32 v84, v84
	v_exp_f32_e32 v85, v85
	v_exp_f32_e32 v86, v86
	v_exp_f32_e32 v87, v87
	v_exp_f32_e32 v88, v88
	v_exp_f32_e32 v89, v89
	v_exp_f32_e32 v90, v90
	v_exp_f32_e32 v91, v91
	v_exp_f32_e32 v92, v92
	v_exp_f32_e32 v93, v93
	v_exp_f32_e32 v94, v94
	v_exp_f32_e32 v95, v95
	v_exp_f32_e32 v96, v96
	v_exp_f32_e32 v97, v97
	v_exp_f32_e32 v98, v98
	v_exp_f32_e32 v99, v99
	v_exp_f32_e32 v100, v100
	v_exp_f32_e32 v101, v101
	v_exp_f32_e32 v102, v102
	v_exp_f32_e32 v103, v103
	v_exp_f32_e32 v104, v104
	v_exp_f32_e32 v105, v105
	v_exp_f32_e32 v106, v106
	v_exp_f32_e32 v107, v107
	v_exp_f32_e32 v108, v108
	v_exp_f32_e32 v109, v109
	v_exp_f32_e32 v110, v110
	v_exp_f32_e32 v111, v111
	v_pk_add_f32 v[42:43], v[72:73], v[74:75]
	v_pk_add_f32 v[44:45], v[76:77], v[78:79]
	v_pk_add_f32 v[42:43], v[42:43], v[80:81]
	v_pk_add_f32 v[44:45], v[44:45], v[82:83]
	v_pk_add_f32 v[42:43], v[42:43], v[84:85]
	v_pk_add_f32 v[44:45], v[44:45], v[86:87]
	v_pk_add_f32 v[42:43], v[42:43], v[88:89]
	v_pk_add_f32 v[44:45], v[44:45], v[90:91]
	v_pk_add_f32 v[42:43], v[42:43], v[92:93]
	v_pk_add_f32 v[44:45], v[44:45], v[94:95]
	v_pk_add_f32 v[42:43], v[42:43], v[96:97]
	v_pk_add_f32 v[44:45], v[44:45], v[98:99]
	v_pk_add_f32 v[42:43], v[42:43], v[100:101]
	v_pk_add_f32 v[44:45], v[44:45], v[102:103]
	v_pk_add_f32 v[42:43], v[42:43], v[104:105]
	v_pk_add_f32 v[44:45], v[44:45], v[106:107]
	v_pk_add_f32 v[42:43], v[42:43], v[108:109]
	v_pk_add_f32 v[44:45], v[44:45], v[110:111]
	v_cvt_pk_bf16_f32 v72, v72, v73
	v_cvt_pk_bf16_f32 v73, v74, v75
	v_cvt_pk_bf16_f32 v74, v76, v77
	v_cvt_pk_bf16_f32 v75, v78, v79
	v_cvt_pk_bf16_f32 v80, v80, v81
	v_cvt_pk_bf16_f32 v81, v82, v83
	v_cvt_pk_bf16_f32 v82, v84, v85
	v_cvt_pk_bf16_f32 v83, v86, v87
	v_cvt_pk_bf16_f32 v88, v88, v89
	v_cvt_pk_bf16_f32 v89, v90, v91
	v_cvt_pk_bf16_f32 v90, v92, v93
	v_cvt_pk_bf16_f32 v91, v94, v95
	v_cvt_pk_bf16_f32 v96, v96, v97
	v_cvt_pk_bf16_f32 v97, v98, v99
	v_cvt_pk_bf16_f32 v98, v100, v101
	v_cvt_pk_bf16_f32 v99, v102, v103
	v_cvt_pk_bf16_f32 v104, v104, v105
	v_cvt_pk_bf16_f32 v105, v106, v107
	v_cvt_pk_bf16_f32 v106, v108, v109
	v_cvt_pk_bf16_f32 v107, v110, v111
	ds_read_b64_tr_b16 v[168:169], v23 offset:0
	ds_read_b64_tr_b16 v[170:171], v23 offset:2048
	ds_read_b64_tr_b16 v[172:173], v24 offset:0
	ds_read_b64_tr_b16 v[174:175], v24 offset:2048
	ds_read_b64_tr_b16 v[196:197], v25 offset:0
	ds_read_b64_tr_b16 v[198:199], v25 offset:2048
	ds_read_b64_tr_b16 v[200:201], v26 offset:0
	ds_read_b64_tr_b16 v[202:203], v26 offset:2048
	ds_read_b64_tr_b16 v[204:205], v23 offset:4096
	ds_read_b64_tr_b16 v[206:207], v23 offset:6144
	ds_read_b64_tr_b16 v[208:209], v24 offset:4096
	ds_read_b64_tr_b16 v[210:211], v24 offset:6144
	ds_read_b64_tr_b16 v[220:221], v25 offset:4096
	ds_read_b64_tr_b16 v[222:223], v25 offset:6144
	ds_read_b64_tr_b16 v[224:225], v26 offset:4096
	ds_read_b64_tr_b16 v[226:227], v26 offset:6144
	s_waitcnt lgkmcnt(14)
; #define LAS __attribute__((address_space(3)))
; __device__ __forceinline__ unsigned pk_bf16(float lo, float hi) { const f32x2_t f = {lo, hi}; return __builtin_bit_cast(unsigned, __builtin_convertvector(f, bf16x2_t)); }
; __device__ __forceinline__ void phase_attn(const Params& p, int l, LAS unsigned char* ldsb) {
;     ...
;                 for (int j = 0; j < 4; ++j) { const float e = __expf(S[kt][j] - mx[j]); S[kt][j] = e; sm[j] += e; }
; #pragma unroll
;             for (int j = 0; j < 4; ++j) inv[j] = 1.f / (row16_sum(sm[j]) + __expf(sink - mx[j]));
; #pragma unroll
;             for (int kt = 0; kt < 10; ++kt)
; #pragma unroll
;                 for (int j = 0; j < 4; ++j) Pw[(4 * fq + j) * 168 + kt * 16 + fr] = (bf16_t)(pk_bf16(S[kt][j] * inv[j], 0.f) & 0xffffu);
;             asm volatile("s_waitcnt lgkmcnt(0)" ::: "memory");
;             __builtin_amdgcn_wave_barrier();
;             f32x4 O[4];
; #pragma unroll
;             for (int dt = 0; dt < 4; ++dt) O[dt] = (f32x4){0.f, 0.f, 0.f, 0.f};
; #pragma unroll
;             for (int kk = 0; kk < 5; ++kk) {
;                 const bf16x8 pa = *(LAS const bf16x8*)(Pw + fr * 168 + kk * 32 + fq * 8);
; #pragma unroll
;                 for (int dt = 0; dt < 4; ++dt) {
;                     const bf16x8 vb = *(LAS const bf16x8*)(Vt + (dt * 16 + fr) * 264 + kstart + kk * 32 + fq * 8);
;                     O[dt] = __builtin_amdgcn_mfma_f32_16x16x32_bf16(pa, vb, O[dt], 0, 0, 0);
;                 }
;             }
; #pragma unroll
;             for (int dt = 0; dt < 4; ++dt)
; #pragma unroll
;                 for (int j = 0; j < 4; ++j) ATT[(size_t)(tokc + q0 + 4 * fq + j) * 512 + hq * 64 + dt * 16 + fr] = (bf16_t)(pk_bf16(O[dt][j], 0.f) & 0xffffu);
;             asm volatile("s_waitcnt lgkmcnt(0)" ::: "memory");
;             __builtin_amdgcn_wave_barrier();
;         }
	v_mfma_f32_16x16x32_bf16 v[152:155], v[168:171], v[72:75], 0
	s_waitcnt lgkmcnt(12)
	v_mfma_f32_16x16x32_bf16 v[156:159], v[172:175], v[72:75], 0
	s_waitcnt lgkmcnt(10)
	v_mfma_f32_16x16x32_bf16 v[160:163], v[196:199], v[72:75], 0
	s_waitcnt lgkmcnt(8)
	v_mfma_f32_16x16x32_bf16 v[164:167], v[200:203], v[72:75], 0
	v_pk_add_f32 v[42:43], v[42:43], v[44:45]
	v_add_f32_e32 v32, v42, v43
	v_mov_b32_e32 v33, v32
	s_nop 1
	v_permlane16_swap_b32_e32 v32, v33
	s_nop 1
	v_add_f32_e32 v32, v32, v33
	v_mov_b32_e32 v33, v32
	s_nop 1
	v_permlane32_swap_b32_e32 v32, v33
	s_nop 1
	v_add_f32_e32 v32, v32, v33
	v_sub_f32_e32 v33, s83, v31
	v_exp_f32_e32 v33, v33
	s_nop 0
	v_add_f32_e32 v32, v32, v33
	v_rcp_f32_e32 v36, v32
	s_nop 0
	v_fma_f32 v33, -v32, v36, 2.0
	v_mul_f32_e32 v36, v36, v33
	ds_read_b64_tr_b16 v[168:169], v23 offset:8192
	ds_read_b64_tr_b16 v[170:171], v23 offset:10240
	ds_read_b64_tr_b16 v[172:173], v24 offset:8192
	ds_read_b64_tr_b16 v[174:175], v24 offset:10240
	ds_read_b64_tr_b16 v[196:197], v25 offset:8192
	ds_read_b64_tr_b16 v[198:199], v25 offset:10240
	ds_read_b64_tr_b16 v[200:201], v26 offset:8192
	ds_read_b64_tr_b16 v[202:203], v26 offset:10240
	s_waitcnt lgkmcnt(14)
	v_mfma_f32_16x16x32_bf16 v[152:155], v[204:207], v[80:83], v[152:155]
	s_waitcnt lgkmcnt(12)
	v_mfma_f32_16x16x32_bf16 v[156:159], v[208:211], v[80:83], v[156:159]
	s_waitcnt lgkmcnt(10)
	v_mfma_f32_16x16x32_bf16 v[160:163], v[220:223], v[80:83], v[160:163]
	s_waitcnt lgkmcnt(8)
	v_mfma_f32_16x16x32_bf16 v[164:167], v[224:227], v[80:83], v[164:167]
	ds_read_b64_tr_b16 v[204:205], v23 offset:12288
	ds_read_b64_tr_b16 v[206:207], v23 offset:14336
	ds_read_b64_tr_b16 v[208:209], v24 offset:12288
	ds_read_b64_tr_b16 v[210:211], v24 offset:14336
	ds_read_b64_tr_b16 v[220:221], v25 offset:12288
	ds_read_b64_tr_b16 v[222:223], v25 offset:14336
	ds_read_b64_tr_b16 v[224:225], v26 offset:12288
	ds_read_b64_tr_b16 v[226:227], v26 offset:14336
	s_waitcnt lgkmcnt(14)
	v_mfma_f32_16x16x32_bf16 v[152:155], v[168:171], v[88:91], v[152:155]
	s_waitcnt lgkmcnt(12)
	v_mfma_f32_16x16x32_bf16 v[156:159], v[172:175], v[88:91], v[156:159]
	s_waitcnt lgkmcnt(10)
	v_mfma_f32_16x16x32_bf16 v[160:163], v[196:199], v[88:91], v[160:163]
	s_waitcnt lgkmcnt(8)
	v_mfma_f32_16x16x32_bf16 v[164:167], v[200:203], v[88:91], v[164:167]
	ds_read_b64_tr_b16 v[168:169], v23 offset:16384
	ds_read_b64_tr_b16 v[170:171], v23 offset:18432
	ds_read_b64_tr_b16 v[172:173], v24 offset:16384
	ds_read_b64_tr_b16 v[174:175], v24 offset:18432
	ds_read_b64_tr_b16 v[196:197], v25 offset:16384
	ds_read_b64_tr_b16 v[198:199], v25 offset:18432
	ds_read_b64_tr_b16 v[200:201], v26 offset:16384
	ds_read_b64_tr_b16 v[202:203], v26 offset:18432
	s_waitcnt lgkmcnt(14)
	v_mfma_f32_16x16x32_bf16 v[152:155], v[204:207], v[96:99], v[152:155]
	s_waitcnt lgkmcnt(12)
	v_mfma_f32_16x16x32_bf16 v[156:159], v[208:211], v[96:99], v[156:159]
	s_waitcnt lgkmcnt(10)
	v_mfma_f32_16x16x32_bf16 v[160:163], v[220:223], v[96:99], v[160:163]
	s_waitcnt lgkmcnt(8)
	v_mfma_f32_16x16x32_bf16 v[164:167], v[224:227], v[96:99], v[164:167]
	s_waitcnt lgkmcnt(6)
	v_mfma_f32_16x16x32_bf16 v[152:155], v[168:171], v[104:107], v[152:155]
	s_waitcnt lgkmcnt(4)
	v_mfma_f32_16x16x32_bf16 v[156:159], v[172:175], v[104:107], v[156:159]
	s_waitcnt lgkmcnt(2)
	v_mfma_f32_16x16x32_bf16 v[160:163], v[196:199], v[104:107], v[160:163]
	s_waitcnt lgkmcnt(0)
	v_mfma_f32_16x16x32_bf16 v[164:167], v[200:203], v[104:107], v[164:167]
	s_nop 1
	v_pk_mul_f32 v[152:153], v[152:153], v[36:37] op_sel_hi:[1,0]
	v_pk_mul_f32 v[154:155], v[154:155], v[36:37] op_sel_hi:[1,0]
	v_cvt_pk_bf16_f32 v46, v152, v153
	v_cvt_pk_bf16_f32 v47, v154, v155
	global_store_dwordx2 v28, v[46:47], s[42:43] offset:0
	v_pk_mul_f32 v[156:157], v[156:157], v[36:37] op_sel_hi:[1,0]
	v_pk_mul_f32 v[158:159], v[158:159], v[36:37] op_sel_hi:[1,0]
	v_cvt_pk_bf16_f32 v46, v156, v157
	v_cvt_pk_bf16_f32 v47, v158, v159
	global_store_dwordx2 v28, v[46:47], s[42:43] offset:32
	v_pk_mul_f32 v[160:161], v[160:161], v[36:37] op_sel_hi:[1,0]
	v_pk_mul_f32 v[162:163], v[162:163], v[36:37] op_sel_hi:[1,0]
	v_cvt_pk_bf16_f32 v46, v160, v161
	v_cvt_pk_bf16_f32 v47, v162, v163
	global_store_dwordx2 v28, v[46:47], s[42:43] offset:64
	v_pk_mul_f32 v[164:165], v[164:165], v[36:37] op_sel_hi:[1,0]
	v_pk_mul_f32 v[166:167], v[166:167], v[36:37] op_sel_hi:[1,0]
	v_cvt_pk_bf16_f32 v46, v164, v165
	v_cvt_pk_bf16_f32 v47, v166, v167
	global_store_dwordx2 v28, v[46:47], s[42:43] offset:96
	s_waitcnt vmcnt(4)
	s_add_u32 s48, s48, 1
	s_cmp_lt_u32 s48, 8
	s_cbranch_scc1 .Lat_rt
